# grid barrier: non-leader workgroups poll the cross-XCC release generation directly (one hop less)
# speedup vs baseline: 1.0059x; 1.0028x over previous
; __device__ __forceinline__ unsigned xb_ld(unsigned* p)              { return __hip_atomic_load(p, __ATOMIC_RELAXED, __HIP_MEMORY_SCOPE_AGENT); }
; __device__ __forceinline__ unsigned xb_add(unsigned* p, unsigned v) { return __hip_atomic_fetch_add(p, v, __ATOMIC_RELAXED, __HIP_MEMORY_SCOPE_AGENT); }
; #define XB_SPIN(cond, bar) do { unsigned _sp = 0; while (cond) { __builtin_amdgcn_s_sleep(1); \
;     if ((++_sp & 255u) == 0u) { if (xb_ld(&(bar)[XB_TMO])) break; if (_sp > XB_SPIN_CAP) { atomicAdd(&(bar)[XB_TMO], 1u); break; } } } } while (0)
; __device__ __forceinline__ void xcd_barrier(const XcdBarrier& b) {
;     ...
;         const unsigned old = xb_add(&bar[XB_XSUB(b.x)], 1u);
;         const unsigned gen = old / nloc;
;         if (old + 1u == (gen + 1u) * nloc) {
;             __builtin_amdgcn_fence(__ATOMIC_RELEASE, "agent");
;             asm volatile("s_waitcnt vmcnt(0)" ::: "memory");
;             const unsigned og = xb_add(&bar[XB_TOP], 1u);
;             const unsigned tg = og / nx;
;             if (og + 1u == (tg + 1u) * nx) xb_add(&bar[XB_TOPGEN], 1u);
;             else XB_SPIN(xb_ld(&bar[XB_TOPGEN]) == tg, bar);
;             __builtin_amdgcn_fence(__ATOMIC_ACQUIRE, "agent");
;             xb_add(&bar[XB_XGEN(b.x)], 1u);
;             asm volatile("s_waitcnt vmcnt(0)" ::: "memory");
;         } else {
;             XB_SPIN(xb_ld(&bar[XB_XGEN(b.x)]) == gen, bar);
;             __builtin_amdgcn_fence(__ATOMIC_ACQUIRE, "agent");
;             asm volatile("s_waitcnt vmcnt(0)" ::: "memory");
;         }
.LBB9_100:
	s_or_b64 exec, exec, s[10:11]
	v_cvt_f32_u32_e32 v4, v2
	s_waitcnt vmcnt(0)
	v_readfirstlane_b32 s2, v3
	v_sub_u32_e32 v3, 0, v2
	v_rcp_iflag_f32_e32 v4, v4
	v_add_u32_e32 v5, s2, v1
	v_mul_f32_e32 v4, 0x4f7ffffe, v4
	v_cvt_u32_f32_e32 v4, v4
	v_mul_lo_u32 v1, v3, v4
	v_mul_hi_u32 v1, v4, v1
	v_add_u32_e32 v1, v4, v1
	v_mul_hi_u32 v1, v5, v1
	v_mul_lo_u32 v3, v1, v2
	v_sub_u32_e32 v3, v5, v3
	v_add_u32_e32 v4, 1, v1
	v_cmp_ge_u32_e32 vcc, v3, v2
	s_nop 1
	v_cndmask_b32_e32 v1, v1, v4, vcc
	v_sub_u32_e32 v4, v3, v2
	v_cndmask_b32_e32 v3, v3, v4, vcc
	v_add_u32_e32 v4, 1, v1
	v_cmp_ge_u32_e32 vcc, v3, v2
	v_add_u32_e32 v3, 1, v5
	s_nop 0
	v_cndmask_b32_e32 v1, v1, v4, vcc
	v_mul_lo_u32 v4, v2, v1
	v_add_u32_e32 v2, v4, v2
	v_cmp_ne_u32_e32 vcc, v3, v2
	s_and_saveexec_b64 s[2:3], vcc
	s_xor_b64 s[10:11], exec, s[2:3]
	s_cbranch_execz .LBB9_114
	s_waitcnt lgkmcnt(0)
	buffer_inv sc1
	v_mov_b32_e32 v0, 0x3100
	global_load_dword v0, v0, s[90:91] offset:1024 sc1
	s_add_u32 s16, s90, 0x3500
	s_addc_u32 s17, s91, 0
	s_waitcnt vmcnt(0)
	v_cmp_eq_u32_e32 vcc, v0, v1
	s_and_saveexec_b64 s[12:13], vcc
	s_cbranch_execz .LBB9_113
	s_mov_b32 s28, 1
	s_mov_b64 s[18:19], 0
	v_mov_b32_e32 v0, 0
	s_branch .LBB9_104

; __device__ __forceinline__ unsigned xb_ld(unsigned* p)              { return __hip_atomic_load(p, __ATOMIC_RELAXED, __HIP_MEMORY_SCOPE_AGENT); }
; __device__ __forceinline__ unsigned xb_add(unsigned* p, unsigned v) { return __hip_atomic_fetch_add(p, v, __ATOMIC_RELAXED, __HIP_MEMORY_SCOPE_AGENT); }
; #define XB_SPIN(cond, bar) do { unsigned _sp = 0; while (cond) { __builtin_amdgcn_s_sleep(1); \
;     if ((++_sp & 255u) == 0u) { if (xb_ld(&(bar)[XB_TMO])) break; if (_sp > XB_SPIN_CAP) { atomicAdd(&(bar)[XB_TMO], 1u); break; } } } } while (0)
; __device__ __forceinline__ void xcd_barrier(const XcdBarrier& b) {
;     ...
;         const unsigned old = xb_add(&bar[XB_XSUB(b.x)], 1u);
;         const unsigned gen = old / nloc;
;         if (old + 1u == (gen + 1u) * nloc) {
;             __builtin_amdgcn_fence(__ATOMIC_RELEASE, "agent");
;             asm volatile("s_waitcnt vmcnt(0)" ::: "memory");
;             const unsigned og = xb_add(&bar[XB_TOP], 1u);
;             const unsigned tg = og / nx;
;             if (og + 1u == (tg + 1u) * nx) xb_add(&bar[XB_TOPGEN], 1u);
;             else XB_SPIN(xb_ld(&bar[XB_TOPGEN]) == tg, bar);
;             __builtin_amdgcn_fence(__ATOMIC_ACQUIRE, "agent");
;             xb_add(&bar[XB_XGEN(b.x)], 1u);
;             asm volatile("s_waitcnt vmcnt(0)" ::: "memory");
;         } else {
;             XB_SPIN(xb_ld(&bar[XB_XGEN(b.x)]) == gen, bar);
;             __builtin_amdgcn_fence(__ATOMIC_ACQUIRE, "agent");
;             asm volatile("s_waitcnt vmcnt(0)" ::: "memory");
;         }
.LBB9_169:
	s_or_b64 exec, exec, s[8:9]
	v_cvt_f32_u32_e32 v4, v2
	s_waitcnt vmcnt(0)
	v_readfirstlane_b32 s2, v3
	v_sub_u32_e32 v3, 0, v2
	v_rcp_iflag_f32_e32 v4, v4
	v_add_u32_e32 v5, s2, v1
	v_mul_f32_e32 v4, 0x4f7ffffe, v4
	v_cvt_u32_f32_e32 v4, v4
	v_mul_lo_u32 v1, v3, v4
	v_mul_hi_u32 v1, v4, v1
	v_add_u32_e32 v1, v4, v1
	v_mul_hi_u32 v1, v5, v1
	v_mul_lo_u32 v3, v1, v2
	v_sub_u32_e32 v3, v5, v3
	v_add_u32_e32 v4, 1, v1
	v_cmp_ge_u32_e32 vcc, v3, v2
	s_nop 1
	v_cndmask_b32_e32 v1, v1, v4, vcc
	v_sub_u32_e32 v4, v3, v2
	v_cndmask_b32_e32 v3, v3, v4, vcc
	v_add_u32_e32 v4, 1, v1
	v_cmp_ge_u32_e32 vcc, v3, v2
	v_add_u32_e32 v3, 1, v5
	s_nop 0
	v_cndmask_b32_e32 v1, v1, v4, vcc
	v_mul_lo_u32 v4, v2, v1
	v_add_u32_e32 v2, v4, v2
	v_cmp_ne_u32_e32 vcc, v3, v2
	s_and_saveexec_b64 s[2:3], vcc
	s_xor_b64 s[8:9], exec, s[2:3]
	s_cbranch_execz .LBB9_183
	s_waitcnt lgkmcnt(0)
	buffer_inv sc1
	v_mov_b32_e32 v0, 0x3100
	global_load_dword v0, v0, s[90:91] offset:1024 sc1
	s_add_u32 s12, s90, 0x3500
	s_addc_u32 s13, s91, 0
	s_waitcnt vmcnt(0)
	v_cmp_eq_u32_e32 vcc, v0, v1
	s_and_saveexec_b64 s[10:11], vcc
	s_cbranch_execz .LBB9_182
	s_mov_b32 s24, 1
	s_mov_b64 s[16:17], 0
	v_mov_b32_e32 v0, 0
	s_branch .LBB9_173

; __device__ __forceinline__ unsigned xb_ld(unsigned* p)              { return __hip_atomic_load(p, __ATOMIC_RELAXED, __HIP_MEMORY_SCOPE_AGENT); }
; __device__ __forceinline__ unsigned xb_add(unsigned* p, unsigned v) { return __hip_atomic_fetch_add(p, v, __ATOMIC_RELAXED, __HIP_MEMORY_SCOPE_AGENT); }
; #define XB_SPIN(cond, bar) do { unsigned _sp = 0; while (cond) { __builtin_amdgcn_s_sleep(1); \
;     if ((++_sp & 255u) == 0u) { if (xb_ld(&(bar)[XB_TMO])) break; if (_sp > XB_SPIN_CAP) { atomicAdd(&(bar)[XB_TMO], 1u); break; } } } } while (0)
; __device__ __forceinline__ void xcd_barrier(const XcdBarrier& b) {
;     ...
;         const unsigned old = xb_add(&bar[XB_XSUB(b.x)], 1u);
;         const unsigned gen = old / nloc;
;         if (old + 1u == (gen + 1u) * nloc) {
;             __builtin_amdgcn_fence(__ATOMIC_RELEASE, "agent");
;             asm volatile("s_waitcnt vmcnt(0)" ::: "memory");
;             const unsigned og = xb_add(&bar[XB_TOP], 1u);
;             const unsigned tg = og / nx;
;             if (og + 1u == (tg + 1u) * nx) xb_add(&bar[XB_TOPGEN], 1u);
;             else XB_SPIN(xb_ld(&bar[XB_TOPGEN]) == tg, bar);
;             __builtin_amdgcn_fence(__ATOMIC_ACQUIRE, "agent");
;             xb_add(&bar[XB_XGEN(b.x)], 1u);
;             asm volatile("s_waitcnt vmcnt(0)" ::: "memory");
;         } else {
;             XB_SPIN(xb_ld(&bar[XB_XGEN(b.x)]) == gen, bar);
;             __builtin_amdgcn_fence(__ATOMIC_ACQUIRE, "agent");
;             asm volatile("s_waitcnt vmcnt(0)" ::: "memory");
;         }
.LBB9_270:
	s_or_b64 exec, exec, s[8:9]
	v_cvt_f32_u32_e32 v4, v2
	s_waitcnt vmcnt(0)
	v_readfirstlane_b32 s2, v3
	v_sub_u32_e32 v3, 0, v2
	v_rcp_iflag_f32_e32 v4, v4
	v_add_u32_e32 v5, s2, v1
	v_mul_f32_e32 v4, 0x4f7ffffe, v4
	v_cvt_u32_f32_e32 v4, v4
	v_mul_lo_u32 v1, v3, v4
	v_mul_hi_u32 v1, v4, v1
	v_add_u32_e32 v1, v4, v1
	v_mul_hi_u32 v1, v5, v1
	v_mul_lo_u32 v3, v1, v2
	v_sub_u32_e32 v3, v5, v3
	v_add_u32_e32 v4, 1, v1
	v_cmp_ge_u32_e32 vcc, v3, v2
	s_nop 1
	v_cndmask_b32_e32 v1, v1, v4, vcc
	v_sub_u32_e32 v4, v3, v2
	v_cndmask_b32_e32 v3, v3, v4, vcc
	v_add_u32_e32 v4, 1, v1
	v_cmp_ge_u32_e32 vcc, v3, v2
	v_add_u32_e32 v3, 1, v5
	s_nop 0
	v_cndmask_b32_e32 v1, v1, v4, vcc
	v_mul_lo_u32 v4, v2, v1
	v_add_u32_e32 v2, v4, v2
	v_cmp_ne_u32_e32 vcc, v3, v2
	s_and_saveexec_b64 s[2:3], vcc
	s_xor_b64 s[8:9], exec, s[2:3]
	s_cbranch_execz .LBB9_284
	s_waitcnt lgkmcnt(0)
	buffer_inv sc1
	v_mov_b32_e32 v0, 0x3100
	global_load_dword v0, v0, s[90:91] offset:1024 sc1
	s_add_u32 s12, s90, 0x3500
	s_addc_u32 s13, s91, 0
	s_waitcnt vmcnt(0)
	v_cmp_eq_u32_e32 vcc, v0, v1
	s_and_saveexec_b64 s[10:11], vcc
	s_cbranch_execz .LBB9_283
	s_mov_b32 s22, 1
	s_mov_b64 s[14:15], 0
	v_mov_b32_e32 v0, 0
	s_branch .LBB9_274
